# mix3 HGRN: batched LDS fragment reads in A.V/state-update; mix1 retention loop: two chunks of K/V loads in flight
# speedup vs baseline: 1.0048x; 1.0048x over previous
.LBB0_832:
	v_cvt_f32_u32_e32 v18, s49
	s_mov_b32 s14, 0xc2fc0000
	v_sub_u32_e32 v20, 63, v22
	v_cvt_f32_i32_e32 v20, v20
	v_sub_f32_e32 v18, 0xc0a00000, v18
	v_cmp_gt_f32_e32 vcc, s14, v18
	s_and_b64 s[14:15], vcc, exec
	s_cselect_b32 s14, 0xffffffc0, 0
	v_cndmask_b32_e32 v19, 0, v246, vcc
	v_add_f32_e32 v18, v18, v19
	v_exp_f32_e32 v18, v18
	s_and_b64 s[0:1], s[0:1], exec
	s_mov_b32 s0, 0x800000
	v_sub_u32_e32 v21, 62, v22
	v_ldexp_f32 v18, v18, s14
	v_sub_f32_e32 v18, 1.0, v18
	v_cmp_gt_f32_e32 vcc, s0, v18
	s_cselect_b32 s14, 4, 1
	s_and_b64 s[0:1], vcc, exec
	s_cselect_b32 s0, 32, 0
	v_ldexp_f32 v18, v18, s0
	v_log_f32_e32 v18, v18
	v_cvt_f32_i32_e32 v21, v21
	v_cndmask_b32_e32 v19, 0, v247, vcc
	v_mul_u32_u24_e32 v24, 0x90, v24
	v_sub_f32_e32 v18, v18, v19
	v_mul_f32_e32 v19, v18, v20
	v_exp_f32_e32 v53, v19
	v_mul_f32_e32 v19, v18, v21
	v_exp_f32_e32 v90, v19
	v_lshrrev_b32_e32 v19, 2, v25
	v_xor_b32_e32 v19, v19, v23
	v_lshlrev_b32_e32 v19, 4, v19
	v_lshlrev_b32_e32 v20, 2, v25
	v_mul_f32_e32 v18, 0x42800000, v18
	v_and_b32_e32 v19, 0x70, v19
	v_and_b32_e32 v20, 12, v20
	v_exp_f32_e32 v92, v18
	v_or_b32_e32 v18, s6, v57
	s_movk_i32 s0, 0x80
	v_mul_lo_u32 v21, v18, s89
	v_lshrrev_b32_e32 v18, 3, v18
	v_lshrrev_b32_e32 v25, 3, v57
	v_or3_b32 v19, v20, v19, v24
	v_or_b32_e32 v24, 4, v56
	v_cmp_gt_i32_e32 vcc, s0, v23
	s_add_i32 s0, 0, 0x18000
	v_or_b32_e32 v26, 2, v25
	v_or_b32_e32 v27, 6, v25
	v_bitop3_b32 v20, v18, v56, 7 bitop3:0x6c
	v_bitop3_b32 v18, v18, v24, 7 bitop3:0x6c
	v_lshl_add_u32 v91, v23, 2, s0
	v_add_u32_e32 v21, 0, v21
	v_lshlrev_b32_e32 v23, 4, v56
	v_lshlrev_b32_e32 v18, 4, v18
	v_xor_b32_e32 v28, v56, v25
	v_bitop3_b32 v29, v56, v25, 4 bitop3:0x36
	v_bitop3_b32 v30, v25, v56, 2 bitop3:0x36
	v_bitop3_b32 v26, v56, v26, 4 bitop3:0x36
	v_bitop3_b32 v31, v25, v56, 4 bitop3:0x36
	v_bitop3_b32 v32, v56, v25, 4 bitop3:0x14
	v_bitop3_b32 v25, v25, v56, 6 bitop3:0x36
	v_bitop3_b32 v27, v56, v27, 4 bitop3:0x36
	v_mov_b32_e32 v36, 0
	v_lshlrev_b32_e32 v20, 4, v20
	v_mad_u32_u24 v24, v57, s89, 0
	v_lshlrev_b32_e32 v28, 4, v28
	v_lshlrev_b32_e32 v29, 4, v29
	v_lshlrev_b32_e32 v30, 4, v30
	v_lshlrev_b32_e32 v26, 4, v26
	v_lshlrev_b32_e32 v31, 4, v31
	v_lshlrev_b32_e32 v32, 4, v32
	v_lshlrev_b32_e32 v25, 4, v25
	v_lshlrev_b32_e32 v27, 4, v27
	s_addk_i32 s50, 0x41
	v_add_u32_e32 v95, v21, v18
	v_add_u32_e32 v18, 0, v23
	s_mov_b32 s7, 0
	v_add_u32_e32 v54, s50, v22
	v_add_u32_e32 v93, 0, v19
	v_add_u32_e32 v94, v21, v20
	v_add_u32_e32 v96, 0x18000, v18
	v_add_u32_e32 v97, v24, v28
	v_add_u32_e32 v98, v24, v29
	v_add_u32_e32 v99, v24, v30
	v_add_u32_e32 v100, v24, v26
	v_add_u32_e32 v101, v24, v31
	v_add_u32_e32 v102, v24, v32
	v_add_u32_e32 v103, v24, v25
	v_add_u32_e32 v104, v24, v27
	v_mov_b32_e32 v37, v36
	v_mov_b32_e32 v38, v36
	v_mov_b32_e32 v39, v36
	v_mov_b32_e32 v48, v36
	v_mov_b32_e32 v49, v36
	v_mov_b32_e32 v50, v36
	v_mov_b32_e32 v51, v36
	v_mov_b32_e32 v44, v36
	v_mov_b32_e32 v45, v36
	v_mov_b32_e32 v46, v36
	v_mov_b32_e32 v47, v36
	v_mov_b32_e32 v40, v36
	v_mov_b32_e32 v41, v36
	v_mov_b32_e32 v42, v36
	v_mov_b32_e32 v43, v36
	v_mov_b32_e32 v30, v36
	v_mov_b32_e32 v31, v36
	v_mov_b32_e32 v32, v36
	v_mov_b32_e32 v33, v36
	v_mov_b32_e32 v26, v36
	v_mov_b32_e32 v27, v36
	v_mov_b32_e32 v28, v36
	v_mov_b32_e32 v29, v36
	v_mov_b32_e32 v22, v36
	v_mov_b32_e32 v23, v36
	v_mov_b32_e32 v24, v36
	v_mov_b32_e32 v25, v36
	v_mov_b32_e32 v18, v36
	v_mov_b32_e32 v19, v36
	v_mov_b32_e32 v20, v36
	v_mov_b32_e32 v21, v36
	s_cmp_gt_u32 s14, 1
	s_cbranch_scc0 .Lp1r_A
	v_add_u32_e32 v198, -1, v54
	v_ashrrev_i32_e32 v199, 31, v198
	v_ashrrev_i32_e32 v55, 31, v54
	v_lshlrev_b64 v[198:199], 14, v[198:199]
	v_lshlrev_b64 v[200:201], 14, v[54:55]
	v_lshl_add_u64 v[206:207], s[36:37], 0, v[198:199]
	v_lshl_add_u64 v[208:209], s[36:37], 0, v[200:201]
	v_lshl_add_u64 v[198:199], v[206:207], 0, s[10:11]
	v_lshl_add_u64 v[200:201], v[208:209], 0, s[10:11]
	v_lshl_add_u64 v[206:207], v[206:207], 0, s[4:5]
	v_lshl_add_u64 v[208:209], v[208:209], 0, s[4:5]
	v_lshl_add_u64 v[198:199], v[198:199], 0, v[34:35]
	v_lshl_add_u64 v[202:203], v[200:201], 0, v[34:35]
	v_lshl_add_u64 v[206:207], v[206:207], 0, v[34:35]
	v_lshl_add_u64 v[210:211], v[208:209], 0, v[34:35]
	global_load_dwordx4 v[198:201], v[198:199], off
	s_nop 0
	global_load_dwordx4 v[202:205], v[202:203], off
	s_nop 0
	global_load_dwordx4 v[206:209], v[206:207], off
	s_nop 0
	global_load_dwordx4 v[210:213], v[210:211], off
	v_add_u32_e32 v54, 64, v54
.Lp1r_A:
	s_and_saveexec_b64 s[0:1], vcc
	ds_write_b32 v91, v92
	s_or_b64 exec, exec, s[0:1]
	s_add_i32 s0, s7, 1
	s_cmp_lt_u32 s0, s14
	s_cbranch_scc1 .Lp1r_Aw
	s_waitcnt vmcnt(0)
	s_branch .Lp1r_Ab

.Lp1r_Ab:
	v_lshlrev_b32_e32 v55, 16, v2
	v_lshlrev_b32_e32 v105, 16, v6
	v_mul_f32_e32 v55, v53, v55
	v_mul_f32_e32 v105, v90, v105
	v_cvt_pk_bf16_f32 v55, v55, v105
	v_and_b32_e32 v105, 0xffff, v10
	v_lshl_or_b32 v105, v14, 16, v105
	ds_write2st64_b32 v93, v55, v105 offset1:72
	v_and_b32_e32 v55, 0xffff0000, v2
	v_and_b32_e32 v105, 0xffff0000, v6
	v_mul_f32_e32 v55, v53, v55
	v_mul_f32_e32 v105, v90, v105
	v_cvt_pk_bf16_f32 v55, v55, v105
	v_lshrrev_b32_e32 v105, 16, v10
	v_and_or_b32 v105, v14, s90, v105
	v_add_u32_e32 v106, 0x90, v93
	ds_write2st64_b32 v106, v55, v105 offset1:72
	v_lshlrev_b32_e32 v55, 16, v3
	v_lshlrev_b32_e32 v105, 16, v7
	v_mul_f32_e32 v55, v53, v55
	v_mul_f32_e32 v105, v90, v105
	v_cvt_pk_bf16_f32 v55, v55, v105
	v_and_b32_e32 v105, 0xffff, v11
	v_lshl_or_b32 v105, v15, 16, v105
	v_add_u32_e32 v106, 32, v93
	ds_write2st64_b32 v106, v55, v105 offset0:1 offset1:73
	v_and_b32_e32 v55, 0xffff0000, v3
	v_and_b32_e32 v105, 0xffff0000, v7
	v_mul_f32_e32 v55, v53, v55
	v_mul_f32_e32 v105, v90, v105
	v_cvt_pk_bf16_f32 v55, v55, v105
	v_lshrrev_b32_e32 v105, 16, v11
	v_and_or_b32 v105, v15, s90, v105
	v_add_u32_e32 v106, 0xb0, v93
	ds_write2st64_b32 v106, v55, v105 offset0:1 offset1:73
	v_lshlrev_b32_e32 v55, 16, v4
	v_lshlrev_b32_e32 v105, 16, v8
	v_mul_f32_e32 v55, v53, v55
	v_mul_f32_e32 v105, v90, v105
	v_cvt_pk_bf16_f32 v55, v55, v105
	v_and_b32_e32 v105, 0xffff, v12
	v_lshl_or_b32 v105, v16, 16, v105
	v_add_u32_e32 v106, 64, v93
	ds_write2st64_b32 v106, v55, v105 offset0:2 offset1:74
	v_and_b32_e32 v55, 0xffff0000, v4
	v_and_b32_e32 v105, 0xffff0000, v8
	v_mul_f32_e32 v55, v53, v55
	v_mul_f32_e32 v105, v90, v105
	v_cvt_pk_bf16_f32 v55, v55, v105
	v_lshrrev_b32_e32 v105, 16, v12
	v_and_or_b32 v105, v16, s90, v105
	v_add_u32_e32 v106, 0xd0, v93
	ds_write2st64_b32 v106, v55, v105 offset0:2 offset1:74
	v_lshlrev_b32_e32 v55, 16, v5
	v_lshlrev_b32_e32 v105, 16, v9
	v_mul_f32_e32 v55, v53, v55
	v_mul_f32_e32 v105, v90, v105
	v_cvt_pk_bf16_f32 v55, v55, v105
	v_and_b32_e32 v105, 0xffff, v13
	v_lshl_or_b32 v105, v17, 16, v105
	v_add_u32_e32 v106, 0x60, v93
	ds_write2st64_b32 v106, v55, v105 offset0:3 offset1:75
	v_and_b32_e32 v55, 0xffff0000, v5
	v_and_b32_e32 v105, 0xffff0000, v9
	v_mul_f32_e32 v55, v53, v55
	v_mul_f32_e32 v105, v90, v105
	v_cvt_pk_bf16_f32 v55, v55, v105
	v_lshrrev_b32_e32 v105, 16, v13
	s_add_i32 s7, s7, 1
	v_and_or_b32 v105, v17, s90, v105
	v_add_u32_e32 v106, 0xf0, v93
	ds_write2st64_b32 v106, v55, v105 offset0:3 offset1:75
	s_waitcnt lgkmcnt(0)
	s_barrier
	s_add_i32 s0, s7, 1
	s_cmp_lt_u32 s0, s14
	s_cbranch_scc0 .Lp1r_Am
	v_add_u32_e32 v2, -1, v54
	v_ashrrev_i32_e32 v3, 31, v2
	v_ashrrev_i32_e32 v55, 31, v54
	v_lshlrev_b64 v[2:3], 14, v[2:3]
	v_lshlrev_b64 v[4:5], 14, v[54:55]
	v_lshl_add_u64 v[10:11], s[36:37], 0, v[2:3]
	v_lshl_add_u64 v[12:13], s[36:37], 0, v[4:5]
	v_lshl_add_u64 v[2:3], v[10:11], 0, s[10:11]
	v_lshl_add_u64 v[4:5], v[12:13], 0, s[10:11]
	v_lshl_add_u64 v[10:11], v[10:11], 0, s[4:5]
	v_lshl_add_u64 v[12:13], v[12:13], 0, s[4:5]
	v_lshl_add_u64 v[2:3], v[2:3], 0, v[34:35]
	v_lshl_add_u64 v[6:7], v[4:5], 0, v[34:35]
	v_lshl_add_u64 v[10:11], v[10:11], 0, v[34:35]
	v_lshl_add_u64 v[14:15], v[12:13], 0, v[34:35]
	global_load_dwordx4 v[2:5], v[2:3], off
	s_nop 0
	global_load_dwordx4 v[6:9], v[6:7], off
	s_nop 0
	global_load_dwordx4 v[10:13], v[10:11], off
	s_nop 0
	global_load_dwordx4 v[14:17], v[14:15], off
	v_add_u32_e32 v54, 64, v54
.Lp1r_Am:
	ds_read_b128 v[106:109], v94 offset:18432
	ds_read_b128 v[110:113], v95 offset:18432
	ds_read_b128 v[114:117], v97
	ds_read_b128 v[118:121], v98
	ds_read_b128 v[122:125], v96
	ds_read_b128 v[126:129], v96 offset:64
	ds_read_b128 v[130:133], v99 offset:2304
	ds_read_b128 v[134:137], v100 offset:2304
	ds_read_b128 v[138:141], v101 offset:4608
	ds_read_b128 v[142:145], v102 offset:4608
	ds_read_b128 v[146:149], v96 offset:128
	ds_read_b128 v[150:153], v96 offset:192
	ds_read_b128 v[154:157], v103 offset:6912
	ds_read_b128 v[158:161], v104 offset:6912
	s_waitcnt lgkmcnt(9)
	v_pk_mul_f32 v[36:37], v[36:37], v[122:123]
	v_pk_mul_f32 v[38:39], v[38:39], v[124:125]
	s_waitcnt lgkmcnt(8)
	v_pk_mul_f32 v[48:49], v[48:49], v[126:127]
	v_pk_mul_f32 v[50:51], v[50:51], v[128:129]
	s_waitcnt lgkmcnt(3)
	v_pk_mul_f32 v[44:45], v[44:45], v[146:147]
	v_pk_mul_f32 v[46:47], v[46:47], v[148:149]
	s_waitcnt lgkmcnt(2)
	v_pk_mul_f32 v[40:41], v[40:41], v[150:151]
	v_pk_mul_f32 v[42:43], v[42:43], v[152:153]
	v_mfma_f32_16x16x32_bf16 v[36:39], v[114:117], v[106:109], v[36:39]
	v_mfma_f32_16x16x32_bf16 v[48:51], v[130:133], v[106:109], v[48:51]
	v_mfma_f32_16x16x32_bf16 v[44:47], v[138:141], v[106:109], v[44:47]
	s_waitcnt lgkmcnt(1)
	v_mfma_f32_16x16x32_bf16 v[40:43], v[154:157], v[106:109], v[40:43]
	v_mfma_f32_16x16x32_bf16 v[36:39], v[118:121], v[110:113], v[36:39]
	v_mfma_f32_16x16x32_bf16 v[48:51], v[134:137], v[110:113], v[48:51]
	v_mfma_f32_16x16x32_bf16 v[44:47], v[142:145], v[110:113], v[44:47]
	s_waitcnt lgkmcnt(0)
	v_mfma_f32_16x16x32_bf16 v[40:43], v[158:161], v[110:113], v[40:43]
	ds_read_b128 v[114:117], v97 offset:9216
	ds_read_b128 v[118:121], v98 offset:9216
	ds_read_b128 v[122:125], v96 offset:256
	ds_read_b128 v[126:129], v96 offset:320
	ds_read_b128 v[130:133], v99 offset:11520
	ds_read_b128 v[134:137], v100 offset:11520
	ds_read_b128 v[138:141], v101 offset:13824
	ds_read_b128 v[142:145], v102 offset:13824
	ds_read_b128 v[146:149], v96 offset:384
	ds_read_b128 v[150:153], v96 offset:448
	ds_read_b128 v[154:157], v103 offset:16128
	ds_read_b128 v[158:161], v104 offset:16128
	s_waitcnt lgkmcnt(9)
	v_pk_mul_f32 v[30:31], v[30:31], v[122:123]
	v_pk_mul_f32 v[32:33], v[32:33], v[124:125]
	s_waitcnt lgkmcnt(8)
	v_pk_mul_f32 v[26:27], v[26:27], v[126:127]
	v_pk_mul_f32 v[28:29], v[28:29], v[128:129]
	s_waitcnt lgkmcnt(3)
	v_pk_mul_f32 v[22:23], v[22:23], v[146:147]
	v_pk_mul_f32 v[24:25], v[24:25], v[148:149]
	s_waitcnt lgkmcnt(2)
	v_pk_mul_f32 v[18:19], v[18:19], v[150:151]
	v_pk_mul_f32 v[20:21], v[20:21], v[152:153]
	v_mfma_f32_16x16x32_bf16 v[30:33], v[114:117], v[106:109], v[30:33]
	v_mfma_f32_16x16x32_bf16 v[26:29], v[130:133], v[106:109], v[26:29]
	v_mfma_f32_16x16x32_bf16 v[22:25], v[138:141], v[106:109], v[22:25]
	s_waitcnt lgkmcnt(1)
	v_mfma_f32_16x16x32_bf16 v[18:21], v[154:157], v[106:109], v[18:21]
	v_mfma_f32_16x16x32_bf16 v[30:33], v[118:121], v[110:113], v[30:33]
	v_mfma_f32_16x16x32_bf16 v[26:29], v[134:137], v[110:113], v[26:29]
	v_mfma_f32_16x16x32_bf16 v[22:25], v[142:145], v[110:113], v[22:25]
	s_waitcnt lgkmcnt(0)
	v_mfma_f32_16x16x32_bf16 v[18:21], v[158:161], v[110:113], v[18:21]
	s_cmp_eq_u32 s14, s7
	s_barrier
	s_cbranch_scc1 .LBB0_838

.Lp1r_Bb:
	v_lshlrev_b32_e32 v55, 16, v198
	v_lshlrev_b32_e32 v105, 16, v202
	v_mul_f32_e32 v55, v53, v55
	v_mul_f32_e32 v105, v90, v105
	v_cvt_pk_bf16_f32 v55, v55, v105
	v_and_b32_e32 v105, 0xffff, v206
	v_lshl_or_b32 v105, v210, 16, v105
	ds_write2st64_b32 v93, v55, v105 offset1:72
	v_and_b32_e32 v55, 0xffff0000, v198
	v_and_b32_e32 v105, 0xffff0000, v202
	v_mul_f32_e32 v55, v53, v55
	v_mul_f32_e32 v105, v90, v105
	v_cvt_pk_bf16_f32 v55, v55, v105
	v_lshrrev_b32_e32 v105, 16, v206
	v_and_or_b32 v105, v210, s90, v105
	v_add_u32_e32 v106, 0x90, v93
	ds_write2st64_b32 v106, v55, v105 offset1:72
	v_lshlrev_b32_e32 v55, 16, v199
	v_lshlrev_b32_e32 v105, 16, v203
	v_mul_f32_e32 v55, v53, v55
	v_mul_f32_e32 v105, v90, v105
	v_cvt_pk_bf16_f32 v55, v55, v105
	v_and_b32_e32 v105, 0xffff, v207
	v_lshl_or_b32 v105, v211, 16, v105
	v_add_u32_e32 v106, 32, v93
	ds_write2st64_b32 v106, v55, v105 offset0:1 offset1:73
	v_and_b32_e32 v55, 0xffff0000, v199
	v_and_b32_e32 v105, 0xffff0000, v203
	v_mul_f32_e32 v55, v53, v55
	v_mul_f32_e32 v105, v90, v105
	v_cvt_pk_bf16_f32 v55, v55, v105
	v_lshrrev_b32_e32 v105, 16, v207
	v_and_or_b32 v105, v211, s90, v105
	v_add_u32_e32 v106, 0xb0, v93
	ds_write2st64_b32 v106, v55, v105 offset0:1 offset1:73
	v_lshlrev_b32_e32 v55, 16, v200
	v_lshlrev_b32_e32 v105, 16, v204
	v_mul_f32_e32 v55, v53, v55
	v_mul_f32_e32 v105, v90, v105
	v_cvt_pk_bf16_f32 v55, v55, v105
	v_and_b32_e32 v105, 0xffff, v208
	v_lshl_or_b32 v105, v212, 16, v105
	v_add_u32_e32 v106, 64, v93
	ds_write2st64_b32 v106, v55, v105 offset0:2 offset1:74
	v_and_b32_e32 v55, 0xffff0000, v200
	v_and_b32_e32 v105, 0xffff0000, v204
	v_mul_f32_e32 v55, v53, v55
	v_mul_f32_e32 v105, v90, v105
	v_cvt_pk_bf16_f32 v55, v55, v105
	v_lshrrev_b32_e32 v105, 16, v208
	v_and_or_b32 v105, v212, s90, v105
	v_add_u32_e32 v106, 0xd0, v93
	ds_write2st64_b32 v106, v55, v105 offset0:2 offset1:74
	v_lshlrev_b32_e32 v55, 16, v201
	v_lshlrev_b32_e32 v105, 16, v205
	v_mul_f32_e32 v55, v53, v55
	v_mul_f32_e32 v105, v90, v105
	v_cvt_pk_bf16_f32 v55, v55, v105
	v_and_b32_e32 v105, 0xffff, v209
	v_lshl_or_b32 v105, v213, 16, v105
	v_add_u32_e32 v106, 0x60, v93
	ds_write2st64_b32 v106, v55, v105 offset0:3 offset1:75
	v_and_b32_e32 v55, 0xffff0000, v201
	v_and_b32_e32 v105, 0xffff0000, v205
	v_mul_f32_e32 v55, v53, v55
	v_mul_f32_e32 v105, v90, v105
	v_cvt_pk_bf16_f32 v55, v55, v105
	v_lshrrev_b32_e32 v105, 16, v209
	s_add_i32 s7, s7, 1
	v_and_or_b32 v105, v213, s90, v105
	v_add_u32_e32 v106, 0xf0, v93
	ds_write2st64_b32 v106, v55, v105 offset0:3 offset1:75
	s_waitcnt lgkmcnt(0)
	s_barrier
	s_add_i32 s0, s7, 1
	s_cmp_lt_u32 s0, s14
	s_cbranch_scc0 .Lp1r_Bm
	v_add_u32_e32 v198, -1, v54
	v_ashrrev_i32_e32 v199, 31, v198
	v_ashrrev_i32_e32 v55, 31, v54
	v_lshlrev_b64 v[198:199], 14, v[198:199]
	v_lshlrev_b64 v[200:201], 14, v[54:55]
	v_lshl_add_u64 v[206:207], s[36:37], 0, v[198:199]
	v_lshl_add_u64 v[208:209], s[36:37], 0, v[200:201]
	v_lshl_add_u64 v[198:199], v[206:207], 0, s[10:11]
	v_lshl_add_u64 v[200:201], v[208:209], 0, s[10:11]
	v_lshl_add_u64 v[206:207], v[206:207], 0, s[4:5]
	v_lshl_add_u64 v[208:209], v[208:209], 0, s[4:5]
	v_lshl_add_u64 v[198:199], v[198:199], 0, v[34:35]
	v_lshl_add_u64 v[202:203], v[200:201], 0, v[34:35]
	v_lshl_add_u64 v[206:207], v[206:207], 0, v[34:35]
	v_lshl_add_u64 v[210:211], v[208:209], 0, v[34:35]
	global_load_dwordx4 v[198:201], v[198:199], off
	s_nop 0
	global_load_dwordx4 v[202:205], v[202:203], off
	s_nop 0
	global_load_dwordx4 v[206:209], v[206:207], off
	s_nop 0
	global_load_dwordx4 v[210:213], v[210:211], off
	v_add_u32_e32 v54, 64, v54
.Lp1r_Bm:
	ds_read_b128 v[106:109], v94 offset:18432
	ds_read_b128 v[110:113], v95 offset:18432
	ds_read_b128 v[114:117], v97
	ds_read_b128 v[118:121], v98
	ds_read_b128 v[122:125], v96
	ds_read_b128 v[126:129], v96 offset:64
	ds_read_b128 v[130:133], v99 offset:2304
	ds_read_b128 v[134:137], v100 offset:2304
	ds_read_b128 v[138:141], v101 offset:4608
	ds_read_b128 v[142:145], v102 offset:4608
	ds_read_b128 v[146:149], v96 offset:128
	ds_read_b128 v[150:153], v96 offset:192
	ds_read_b128 v[154:157], v103 offset:6912
	ds_read_b128 v[158:161], v104 offset:6912
	s_waitcnt lgkmcnt(9)
	v_pk_mul_f32 v[36:37], v[36:37], v[122:123]
	v_pk_mul_f32 v[38:39], v[38:39], v[124:125]
	s_waitcnt lgkmcnt(8)
	v_pk_mul_f32 v[48:49], v[48:49], v[126:127]
	v_pk_mul_f32 v[50:51], v[50:51], v[128:129]
	s_waitcnt lgkmcnt(3)
	v_pk_mul_f32 v[44:45], v[44:45], v[146:147]
	v_pk_mul_f32 v[46:47], v[46:47], v[148:149]
	s_waitcnt lgkmcnt(2)
	v_pk_mul_f32 v[40:41], v[40:41], v[150:151]
	v_pk_mul_f32 v[42:43], v[42:43], v[152:153]
	v_mfma_f32_16x16x32_bf16 v[36:39], v[114:117], v[106:109], v[36:39]
	v_mfma_f32_16x16x32_bf16 v[48:51], v[130:133], v[106:109], v[48:51]
	v_mfma_f32_16x16x32_bf16 v[44:47], v[138:141], v[106:109], v[44:47]
	s_waitcnt lgkmcnt(1)
	v_mfma_f32_16x16x32_bf16 v[40:43], v[154:157], v[106:109], v[40:43]
	v_mfma_f32_16x16x32_bf16 v[36:39], v[118:121], v[110:113], v[36:39]
	v_mfma_f32_16x16x32_bf16 v[48:51], v[134:137], v[110:113], v[48:51]
	v_mfma_f32_16x16x32_bf16 v[44:47], v[142:145], v[110:113], v[44:47]
	s_waitcnt lgkmcnt(0)
	v_mfma_f32_16x16x32_bf16 v[40:43], v[158:161], v[110:113], v[40:43]
	ds_read_b128 v[114:117], v97 offset:9216
	ds_read_b128 v[118:121], v98 offset:9216
	ds_read_b128 v[122:125], v96 offset:256
	ds_read_b128 v[126:129], v96 offset:320
	ds_read_b128 v[130:133], v99 offset:11520
	ds_read_b128 v[134:137], v100 offset:11520
	ds_read_b128 v[138:141], v101 offset:13824
	ds_read_b128 v[142:145], v102 offset:13824
	ds_read_b128 v[146:149], v96 offset:384
	ds_read_b128 v[150:153], v96 offset:448
	ds_read_b128 v[154:157], v103 offset:16128
	ds_read_b128 v[158:161], v104 offset:16128
	s_waitcnt lgkmcnt(9)
	v_pk_mul_f32 v[30:31], v[30:31], v[122:123]
	v_pk_mul_f32 v[32:33], v[32:33], v[124:125]
	s_waitcnt lgkmcnt(8)
	v_pk_mul_f32 v[26:27], v[26:27], v[126:127]
	v_pk_mul_f32 v[28:29], v[28:29], v[128:129]
	s_waitcnt lgkmcnt(3)
	v_pk_mul_f32 v[22:23], v[22:23], v[146:147]
	v_pk_mul_f32 v[24:25], v[24:25], v[148:149]
	s_waitcnt lgkmcnt(2)
	v_pk_mul_f32 v[18:19], v[18:19], v[150:151]
	v_pk_mul_f32 v[20:21], v[20:21], v[152:153]
	v_mfma_f32_16x16x32_bf16 v[30:33], v[114:117], v[106:109], v[30:33]
	v_mfma_f32_16x16x32_bf16 v[26:29], v[130:133], v[106:109], v[26:29]
	v_mfma_f32_16x16x32_bf16 v[22:25], v[138:141], v[106:109], v[22:25]
	s_waitcnt lgkmcnt(1)
	v_mfma_f32_16x16x32_bf16 v[18:21], v[154:157], v[106:109], v[18:21]
	v_mfma_f32_16x16x32_bf16 v[30:33], v[118:121], v[110:113], v[30:33]
	v_mfma_f32_16x16x32_bf16 v[26:29], v[134:137], v[110:113], v[26:29]
	v_mfma_f32_16x16x32_bf16 v[22:25], v[142:145], v[110:113], v[22:25]
	s_waitcnt lgkmcnt(0)
	v_mfma_f32_16x16x32_bf16 v[18:21], v[158:161], v[110:113], v[18:21]
	s_cmp_eq_u32 s14, s7
	s_barrier
	s_cbranch_scc1 .LBB0_838
	s_branch .Lp1r_A

.LBB0_1126:
	s_nop 7
	v_cndmask_b32_e64 v160, v160, 0, s[54:55]
	v_cndmask_b32_e64 v161, 0, v161, s[56:57]
	v_cvt_pk_bf16_f32 v160, v160, v161
	v_cndmask_b32_e64 v161, v162, 0, s[58:59]
	v_cndmask_b32_e64 v162, v163, 0, s[60:61]
	v_cvt_pk_bf16_f32 v161, v161, v162
	v_cndmask_b32_e64 v160, 0, v160, s[44:45]
	v_cndmask_b32_e64 v161, 0, v161, s[44:45]
	v_add_u32_e32 v186, 0x1000, v230
	v_add_u32_e32 v187, 0x2000, v230
	v_add_u32_e32 v251, 0x3000, v230
	ds_write_b64 v229, v[160:161]
	v_cvt_pk_bf16_f32 v160, v84, v85
	v_cvt_pk_bf16_f32 v161, v86, v87
	v_cvt_pk_bf16_f32 v162, v72, v73
	v_cvt_pk_bf16_f32 v163, v74, v75
	ds_read2_b64 v[164:167], v230 offset1:4
	ds_read2_b64 v[168:171], v186 offset0:32 offset1:36
	ds_read2_b64 v[172:175], v187 offset0:64 offset1:68
	ds_read2_b64 v[176:179], v251 offset0:96 offset1:100
	s_waitcnt lgkmcnt(3)
	v_mfma_f32_16x16x32_bf16 v[164:167], v[160:163], v[164:167], 0
	s_andn2_b64 vcc, exec, s[16:17]
	s_waitcnt lgkmcnt(2)
	v_mfma_f32_16x16x32_bf16 v[168:171], v[160:163], v[168:171], 0
	s_waitcnt lgkmcnt(1)
	v_mfma_f32_16x16x32_bf16 v[172:175], v[160:163], v[172:175], 0
	s_waitcnt lgkmcnt(0)
	v_mfma_f32_16x16x32_bf16 v[160:163], v[160:163], v[176:179], 0
	v_cvt_pk_bf16_f32 v176, v76, v77
	v_cvt_pk_bf16_f32 v177, v78, v79
	v_cvt_pk_bf16_f32 v178, v80, v81
	v_cvt_pk_bf16_f32 v179, v82, v83
	ds_read2_b64 v[180:183], v230 offset0:8 offset1:12
	s_waitcnt lgkmcnt(0)
	v_mfma_f32_16x16x32_bf16 v[164:167], v[176:179], v[180:183], v[164:167]
	ds_read2_b64 v[180:183], v186 offset0:40 offset1:44
	s_waitcnt lgkmcnt(0)
	v_mfma_f32_16x16x32_bf16 v[168:171], v[176:179], v[180:183], v[168:171]
	ds_read2_b64 v[180:183], v187 offset0:72 offset1:76
	s_waitcnt lgkmcnt(0)
	v_mfma_f32_16x16x32_bf16 v[172:175], v[176:179], v[180:183], v[172:175]
	ds_read2_b64 v[180:183], v251 offset0:104 offset1:108
	s_waitcnt lgkmcnt(0)
	v_mfma_f32_16x16x32_bf16 v[160:163], v[176:179], v[180:183], v[160:163]
	v_cvt_pk_bf16_f32 v176, v132, v133
	v_cvt_pk_bf16_f32 v177, v134, v135
	v_cvt_pk_bf16_f32 v178, v100, v101
	v_cvt_pk_bf16_f32 v179, v102, v103
	ds_read2_b64 v[180:183], v230 offset0:16 offset1:20
	s_waitcnt lgkmcnt(0)
	v_mfma_f32_16x16x32_bf16 v[164:167], v[176:179], v[180:183], v[164:167]
	ds_read2_b64 v[180:183], v186 offset0:48 offset1:52
	s_waitcnt lgkmcnt(0)
	v_mfma_f32_16x16x32_bf16 v[168:171], v[176:179], v[180:183], v[168:171]
	ds_read2_b64 v[180:183], v187 offset0:80 offset1:84
	s_waitcnt lgkmcnt(0)
	v_mfma_f32_16x16x32_bf16 v[172:175], v[176:179], v[180:183], v[172:175]
	ds_read2_b64 v[180:183], v251 offset0:112 offset1:116
	s_waitcnt lgkmcnt(0)
	v_mfma_f32_16x16x32_bf16 v[160:163], v[176:179], v[180:183], v[160:163]
	v_cvt_pk_bf16_f32 v176, v108, v109
	v_cvt_pk_bf16_f32 v177, v110, v111
	v_cvt_pk_bf16_f32 v178, v128, v129
	v_cvt_pk_bf16_f32 v179, v130, v131
	ds_read2_b64 v[180:183], v230 offset0:24 offset1:28
	s_waitcnt lgkmcnt(0)
	v_mfma_f32_16x16x32_bf16 v[164:167], v[176:179], v[180:183], v[164:167]
	ds_read2_b64 v[180:183], v186 offset0:56 offset1:60
	s_waitcnt lgkmcnt(0)
	v_mfma_f32_16x16x32_bf16 v[168:171], v[176:179], v[180:183], v[168:171]
	ds_read2_b64 v[180:183], v187 offset0:88 offset1:92
	s_waitcnt lgkmcnt(0)
	v_mfma_f32_16x16x32_bf16 v[186:189], v[176:179], v[180:183], v[172:175]
	s_nop 2
	ds_read2_b64 v[172:175], v251 offset0:120 offset1:124
	s_waitcnt lgkmcnt(0)
	v_mfma_f32_16x16x32_bf16 v[160:163], v[176:179], v[172:175], v[160:163]
	s_barrier
	ds_read_b128 v[180:183], v231 offset:18432
	ds_read_b128 v[176:179], v232 offset:18432
	ds_read_b128 v[36:39], v233
	ds_read_b128 v[40:43], v233 offset:2304
	ds_read_b128 v[44:47], v233 offset:4608
	ds_read_b128 v[48:51], v233 offset:6912
	ds_read_b128 v[52:55], v233 offset:4672
	ds_read_b128 v[56:59], v233 offset:6976
	s_waitcnt lgkmcnt(5)
	v_mfma_f32_16x16x32_bf16 v[172:175], v[180:183], v[36:39], v[164:167]
	s_waitcnt lgkmcnt(4)
	v_mfma_f32_16x16x32_bf16 v[168:171], v[180:183], v[40:43], v[168:171]
	s_waitcnt lgkmcnt(3)
	v_mfma_f32_16x16x32_bf16 v[164:167], v[180:183], v[44:47], v[186:189]
	s_waitcnt lgkmcnt(2)
	v_mfma_f32_16x16x32_bf16 v[160:163], v[180:183], v[48:51], v[160:163]
	s_waitcnt lgkmcnt(1)
	v_mfma_f32_16x16x32_bf16 v[164:167], v[176:179], v[52:55], v[164:167]
	s_waitcnt lgkmcnt(0)
	v_mfma_f32_16x16x32_bf16 v[160:163], v[176:179], v[56:59], v[160:163]
	s_cbranch_vccnz .LBB0_1128
	ds_read_b128 v[36:39], v213
	ds_read_b128 v[40:43], v234
	ds_read_b128 v[44:47], v235
	ds_read_b128 v[48:51], v213 offset:64
	ds_read_b128 v[52:55], v236 offset:2304
	ds_read_b128 v[56:59], v237 offset:2304
	ds_read_b128 v[60:63], v213 offset:128
	ds_read_b128 v[64:67], v238 offset:4608
	ds_read_b128 v[186:189], v239 offset:4608
	s_waitcnt lgkmcnt(6)
	v_pk_mul_f32 v[86:87], v[86:87], v[38:39]
	v_pk_mul_f32 v[84:85], v[84:85], v[36:37]
	s_nop 1
	v_mfma_f32_16x16x32_bf16 v[84:87], v[40:43], v[180:183], v[84:87]
	v_mfma_f32_16x16x32_bf16 v[84:87], v[44:47], v[176:179], v[84:87]
	ds_read_b128 v[36:39], v213 offset:192
	ds_read_b128 v[40:43], v240 offset:6912
	ds_read_b128 v[44:47], v241 offset:6912
	s_waitcnt lgkmcnt(6)
	v_pk_mul_f32 v[74:75], v[74:75], v[50:51]
	v_pk_mul_f32 v[72:73], v[72:73], v[48:49]
	s_nop 1
	v_mfma_f32_16x16x32_bf16 v[72:75], v[52:55], v[180:183], v[72:75]
	v_mfma_f32_16x16x32_bf16 v[72:75], v[56:59], v[176:179], v[72:75]
	ds_read_b128 v[48:51], v213 offset:256
	ds_read_b128 v[52:55], v234 offset:9216
	ds_read_b128 v[56:59], v235 offset:9216
	s_waitcnt lgkmcnt(6)
	v_pk_mul_f32 v[78:79], v[78:79], v[62:63]
	v_pk_mul_f32 v[76:77], v[76:77], v[60:61]
	s_nop 1
	v_mfma_f32_16x16x32_bf16 v[76:79], v[64:67], v[180:183], v[76:79]
	v_mfma_f32_16x16x32_bf16 v[76:79], v[186:189], v[176:179], v[76:79]
	ds_read_b128 v[60:63], v213 offset:320
	ds_read_b128 v[64:67], v236 offset:11520
	ds_read_b128 v[186:189], v237 offset:11520
	s_waitcnt lgkmcnt(6)
	v_pk_mul_f32 v[82:83], v[82:83], v[38:39]
	v_pk_mul_f32 v[80:81], v[80:81], v[36:37]
	s_nop 1
	v_mfma_f32_16x16x32_bf16 v[80:83], v[40:43], v[180:183], v[80:83]
	v_mfma_f32_16x16x32_bf16 v[80:83], v[44:47], v[176:179], v[80:83]
	ds_read_b128 v[36:39], v213 offset:384
	ds_read_b128 v[40:43], v238 offset:13824
	ds_read_b128 v[44:47], v239 offset:13824
	s_waitcnt lgkmcnt(6)
	v_pk_mul_f32 v[134:135], v[134:135], v[50:51]
	v_pk_mul_f32 v[132:133], v[132:133], v[48:49]
	s_nop 1
	v_mfma_f32_16x16x32_bf16 v[132:135], v[52:55], v[180:183], v[132:135]
	v_mfma_f32_16x16x32_bf16 v[132:135], v[56:59], v[176:179], v[132:135]
	ds_read_b128 v[48:51], v213 offset:448
	ds_read_b128 v[52:55], v240 offset:16128
	ds_read_b128 v[56:59], v241 offset:16128
	s_waitcnt lgkmcnt(6)
	v_pk_mul_f32 v[102:103], v[102:103], v[62:63]
	v_pk_mul_f32 v[100:101], v[100:101], v[60:61]
	s_nop 1
	v_mfma_f32_16x16x32_bf16 v[100:103], v[64:67], v[180:183], v[100:103]
	v_mfma_f32_16x16x32_bf16 v[100:103], v[186:189], v[176:179], v[100:103]
	s_waitcnt lgkmcnt(3)
	v_pk_mul_f32 v[110:111], v[110:111], v[38:39]
	v_pk_mul_f32 v[108:109], v[108:109], v[36:37]
	s_nop 1
	v_mfma_f32_16x16x32_bf16 v[108:111], v[40:43], v[180:183], v[108:111]
	v_mfma_f32_16x16x32_bf16 v[108:111], v[44:47], v[176:179], v[108:111]
	s_waitcnt lgkmcnt(0)
	v_pk_mul_f32 v[130:131], v[130:131], v[50:51]
	v_pk_mul_f32 v[128:129], v[128:129], v[48:49]
	s_nop 1
	v_mfma_f32_16x16x32_bf16 v[128:131], v[52:55], v[180:183], v[128:131]
	v_mfma_f32_16x16x32_bf16 v[128:131], v[56:59], v[176:179], v[128:131]
